# p4 K-loop: removed the compiler's per-iteration vmcnt(0) (false VGPR dependency on mid-hook loads) so the DMA prefetch stays in flight
# speedup vs baseline: 1.0179x; 1.0065x over previous
; #define PG8_STAGE(bufoff, gbase, voff) do { _Pragma("unroll") for (int _i = 0; _i < 2; ++_i) \
;         __builtin_amdgcn_global_load_lds((const unsigned*)((const char*)(gbase) + (voff)[_i]), (LAS unsigned*)(lds + (bufoff) + ldsw + _i * 8192), 16, 0, 0); } while (0)
; #define PG8_LDA(dst, b, h) do { _Pragma("unroll") for (int m = 0; m < 4; ++m) _Pragma("unroll") for (int k = 0; k < 2; ++k) dst[m][k] = *(const LAS bf16x8*)(lds + PG8_SA(b, h) + aoff + m * 2048 + k * 1024); } while (0)
; #define PG8_LDB(dst, b, h) do { _Pragma("unroll") for (int n = 0; n < 2; ++n) _Pragma("unroll") for (int k = 0; k < 2; ++k) dst[n][k] = *(const LAS bf16x8*)(lds + PG8_SB(b, h) + boff + n * 2048 + k * 1024); } while (0)
; #define PG8_MMA(ai, bj, At, Bt) do { __builtin_amdgcn_s_setprio(1); _Pragma("unroll") for (int m = 0; m < 4; ++m) _Pragma("unroll") for (int n = 0; n < 2; ++n) _Pragma("unroll") for (int k = 0; k < 2; ++k) \
;         acc[ai][bj][m][n] = __builtin_amdgcn_mfma_f32_16x16x32_bf16(Bt[n][k], At[m][k], acc[ai][bj][m][n], 0, 0, 0); __builtin_amdgcn_s_setprio(0); } while (0)
; #define PG8_WAIT_L(n) asm volatile("s_waitcnt lgkmcnt(" #n ")" ::: "memory")
; #define PG8_BAR __builtin_amdgcn_s_barrier()
; #define PG8_SCHED __builtin_amdgcn_sched_barrier(0)
; template <class Epi>
; DI void gemm_phase(LAS unsigned char* lds, const Gemm g, const StaticOrder& S, const Epi& E) {
;     ...
;         for (int t = 0; t < nt; t += 2) {
;             const bool last = (t == nt - 2);
;             const char* a1 = cA + (size_t)(t + 1) * kstep;
;             const char* a2 = last ? nA : cA + (size_t)(t + 2) * kstep; const char* b2 = last ? nB : cB + (size_t)(t + 2) * kstep;
;             const char* a3 = a2 + kstep; const char* b3 = b2 + kstep;
;             if constexpr (Epi::HAS_MID) { if (t == Epi::MID_T) E.mid(acc, cur, wr, wc, fr, fq); }
;             PG8_LDB(B0, 0, 0); PG8_SCHED; PG8_LDA(At, 0, 0); PG8_STAGE(PG8_SA(1, 1), a1 + hstepA, voffA);
;             PG8_WAIT_L(8); PG8_BAR; PG8_WAIT_L(0); PG8_MMA(0, 0, At, B0); PG8_BAR; PG8_SCHED;
;             PG8_LDB(B1, 0, 1); PG8_STAGE(PG8_SB(0, 0), b2, voffB);
;             PG8_BAR; PG8_WAIT_L(0); PG8_MMA(0, 1, At, B1); PG8_BAR;
;             PG8_LDA(At, 0, 1); PG8_STAGE(PG8_SA(0, 0), a2, voffA);
;             PG8_BAR; PG8_WAIT_L(0); PG8_MMA(1, 0, At, B0); PG8_BAR; PG8_SCHED;
.LBB0_630:
	v_add_u32_e32 v1, s56, v219
	s_add_u32 s0, s26, s36
	ds_read_b128 v[132:135], v1
	ds_read_b128 v[136:139], v1 offset:1024
	ds_read_b128 v[140:143], v1 offset:2048
	ds_read_b128 v[144:147], v1 offset:3072
	s_addc_u32 s1, s27, s37
	s_add_u32 s0, s0, 0x100
	s_addc_u32 s1, s1, 0
	s_add_u32 s38, s60, s36
	s_addc_u32 s39, s61, s37
	s_cmpk_eq_i32 s36, 0x1f00
	s_cselect_b32 s41, s21, s1
	s_cselect_b32 s40, s58, s0
	s_cselect_b32 s39, s19, s39
	s_cselect_b32 s38, s59, s38
	v_lshl_add_u64 v[2:3], v[206:207], 0, s[36:37]
	s_add_i32 m0, s44, 0xc000
	ds_read_b128 v[148:151], v222
	ds_read_b128 v[152:155], v222 offset:1024
	ds_read_b128 v[156:159], v222 offset:2048
	ds_read_b128 v[160:163], v222 offset:3072
	ds_read_b128 v[164:167], v222 offset:4096
	ds_read_b128 v[168:171], v222 offset:5120
	ds_read_b128 v[172:175], v222 offset:6144
	ds_read_b128 v[176:179], v222 offset:7168
	global_load_lds_dwordx4 v[2:3], off
	v_lshl_add_u64 v[2:3], v[208:209], 0, s[36:37]
	s_add_i32 m0, s44, 0xe000
	s_nop 0
	global_load_lds_dwordx4 v[2:3], off
	s_waitcnt lgkmcnt(8)
	s_barrier
	s_waitcnt lgkmcnt(0)
	s_setprio 1
	s_waitcnt lgkmcnt(0)
	v_mfma_f32_16x16x32_bf16 v[128:131], v[132:135], v[148:151], v[128:131]
	v_mfma_f32_16x16x32_bf16 v[124:127], v[140:143], v[148:151], v[124:127]
	v_mfma_f32_16x16x32_bf16 v[112:115], v[132:135], v[156:159], v[112:115]
	v_mfma_f32_16x16x32_bf16 v[108:111], v[140:143], v[156:159], v[108:111]
	v_mfma_f32_16x16x32_bf16 v[96:99], v[132:135], v[164:167], v[96:99]
	v_mfma_f32_16x16x32_bf16 v[92:95], v[140:143], v[164:167], v[92:95]
	v_mfma_f32_16x16x32_bf16 v[80:83], v[132:135], v[172:175], v[80:83]
	v_mfma_f32_16x16x32_bf16 v[76:79], v[140:143], v[172:175], v[76:79]
	v_mfma_f32_16x16x32_bf16 v[128:131], v[136:139], v[152:155], v[128:131]
	v_mfma_f32_16x16x32_bf16 v[124:127], v[144:147], v[152:155], v[124:127]
	v_mfma_f32_16x16x32_bf16 v[112:115], v[136:139], v[160:163], v[112:115]
	v_mfma_f32_16x16x32_bf16 v[108:111], v[144:147], v[160:163], v[108:111]
	v_mfma_f32_16x16x32_bf16 v[96:99], v[136:139], v[168:171], v[96:99]
	v_mfma_f32_16x16x32_bf16 v[92:95], v[144:147], v[168:171], v[92:95]
	v_mfma_f32_16x16x32_bf16 v[80:83], v[136:139], v[176:179], v[80:83]
	v_mfma_f32_16x16x32_bf16 v[76:79], v[144:147], v[176:179], v[76:79]
	s_setprio 0
	s_barrier
	s_add_i32 s0, s56, s33
	v_add_u32_e32 v1, s57, v219
	v_lshl_add_u64 v[228:229], s[38:39], 0, v[190:191]
	s_mov_b32 m0, s0
	ds_read_b128 v[180:183], v1
	ds_read_b128 v[184:187], v1 offset:1024
	ds_read_b128 v[210:213], v1 offset:2048
	ds_read_b128 v[224:227], v1 offset:3072
	global_load_lds_dwordx4 v[228:229], off
	v_lshl_add_u64 v[230:231], s[38:39], 0, v[194:195]
	s_add_i32 m0, s0, 0x2000
	s_nop 0
	global_load_lds_dwordx4 v[230:231], off
	s_barrier
	s_waitcnt lgkmcnt(0)
	s_setprio 1
	s_waitcnt lgkmcnt(0)
	v_mfma_f32_16x16x32_bf16 v[120:123], v[180:183], v[148:151], v[120:123]
	v_mfma_f32_16x16x32_bf16 v[116:119], v[210:213], v[148:151], v[116:119]
	v_mfma_f32_16x16x32_bf16 v[104:107], v[180:183], v[156:159], v[104:107]
	v_mfma_f32_16x16x32_bf16 v[100:103], v[210:213], v[156:159], v[100:103]
	v_mfma_f32_16x16x32_bf16 v[88:91], v[180:183], v[164:167], v[88:91]
	v_mfma_f32_16x16x32_bf16 v[84:87], v[210:213], v[164:167], v[84:87]
	v_mfma_f32_16x16x32_bf16 v[72:75], v[180:183], v[172:175], v[72:75]
	v_mfma_f32_16x16x32_bf16 v[68:71], v[210:213], v[172:175], v[68:71]
	v_mfma_f32_16x16x32_bf16 v[120:123], v[184:187], v[152:155], v[120:123]
	v_mfma_f32_16x16x32_bf16 v[116:119], v[224:227], v[152:155], v[116:119]
	v_mfma_f32_16x16x32_bf16 v[104:107], v[184:187], v[160:163], v[104:107]
	v_mfma_f32_16x16x32_bf16 v[100:103], v[224:227], v[160:163], v[100:103]
	v_mfma_f32_16x16x32_bf16 v[88:91], v[184:187], v[168:171], v[88:91]
	v_mfma_f32_16x16x32_bf16 v[84:87], v[224:227], v[168:171], v[84:87]
	v_mfma_f32_16x16x32_bf16 v[72:75], v[184:187], v[176:179], v[72:75]
	v_mfma_f32_16x16x32_bf16 v[68:71], v[224:227], v[176:179], v[68:71]
	s_setprio 0
	s_mov_b32 m0, s44
	v_lshl_add_u64 v[232:233], s[40:41], 0, v[188:189]
	s_barrier
	ds_read_b128 v[148:151], v222 offset:16384
	ds_read_b128 v[152:155], v222 offset:17408
	ds_read_b128 v[156:159], v222 offset:18432
	ds_read_b128 v[160:163], v222 offset:19456
	ds_read_b128 v[164:167], v222 offset:20480
	ds_read_b128 v[168:171], v222 offset:21504
	ds_read_b128 v[172:175], v222 offset:22528
	ds_read_b128 v[176:179], v222 offset:23552
	global_load_lds_dwordx4 v[232:233], off
	v_lshl_add_u64 v[234:235], s[40:41], 0, v[192:193]
	s_mov_b32 m0, s45
	s_nop 0
	global_load_lds_dwordx4 v[234:235], off
	s_barrier
	s_waitcnt lgkmcnt(0)
	s_setprio 1
	s_waitcnt lgkmcnt(0)
	v_mfma_f32_16x16x32_bf16 v[64:67], v[132:135], v[148:151], v[64:67]
	v_mfma_f32_16x16x32_bf16 v[60:63], v[140:143], v[148:151], v[60:63]
	v_mfma_f32_16x16x32_bf16 v[48:51], v[132:135], v[156:159], v[48:51]
	v_mfma_f32_16x16x32_bf16 v[44:47], v[140:143], v[156:159], v[44:47]
	v_mfma_f32_16x16x32_bf16 v[32:35], v[132:135], v[164:167], v[32:35]
	v_mfma_f32_16x16x32_bf16 v[28:31], v[140:143], v[164:167], v[28:31]
	v_mfma_f32_16x16x32_bf16 v[16:19], v[132:135], v[172:175], v[16:19]
	v_mfma_f32_16x16x32_bf16 v[12:15], v[140:143], v[172:175], v[12:15]
	v_mfma_f32_16x16x32_bf16 v[64:67], v[136:139], v[152:155], v[64:67]
	v_mfma_f32_16x16x32_bf16 v[60:63], v[144:147], v[152:155], v[60:63]
	v_mfma_f32_16x16x32_bf16 v[48:51], v[136:139], v[160:163], v[48:51]
	v_mfma_f32_16x16x32_bf16 v[44:47], v[144:147], v[160:163], v[44:47]
	v_mfma_f32_16x16x32_bf16 v[32:35], v[136:139], v[168:171], v[32:35]
	v_mfma_f32_16x16x32_bf16 v[28:31], v[144:147], v[168:171], v[28:31]
	v_mfma_f32_16x16x32_bf16 v[16:19], v[136:139], v[176:179], v[16:19]
	v_mfma_f32_16x16x32_bf16 v[12:15], v[144:147], v[176:179], v[12:15]
	s_setprio 0
	s_barrier
; #define PG8_STAGE(bufoff, gbase, voff) do { _Pragma("unroll") for (int _i = 0; _i < 2; ++_i) \
;         __builtin_amdgcn_global_load_lds((const unsigned*)((const char*)(gbase) + (voff)[_i]), (LAS unsigned*)(lds + (bufoff) + ldsw + _i * 8192), 16, 0, 0); } while (0)
; #define PG8_LDA(dst, b, h) do { _Pragma("unroll") for (int m = 0; m < 4; ++m) _Pragma("unroll") for (int k = 0; k < 2; ++k) dst[m][k] = *(const LAS bf16x8*)(lds + PG8_SA(b, h) + aoff + m * 2048 + k * 1024); } while (0)
; #define PG8_LDB(dst, b, h) do { _Pragma("unroll") for (int n = 0; n < 2; ++n) _Pragma("unroll") for (int k = 0; k < 2; ++k) dst[n][k] = *(const LAS bf16x8*)(lds + PG8_SB(b, h) + boff + n * 2048 + k * 1024); } while (0)
; #define PG8_MMA(ai, bj, At, Bt) do { __builtin_amdgcn_s_setprio(1); _Pragma("unroll") for (int m = 0; m < 4; ++m) _Pragma("unroll") for (int n = 0; n < 2; ++n) _Pragma("unroll") for (int k = 0; k < 2; ++k) \
;         acc[ai][bj][m][n] = __builtin_amdgcn_mfma_f32_16x16x32_bf16(Bt[n][k], At[m][k], acc[ai][bj][m][n], 0, 0, 0); __builtin_amdgcn_s_setprio(0); } while (0)
; #define PG8_WAIT_V(n) asm volatile("s_waitcnt vmcnt(" #n ")" ::: "memory")
; #define PG8_WAIT_L(n) asm volatile("s_waitcnt lgkmcnt(" #n ")" ::: "memory")
; #define PG8_BAR __builtin_amdgcn_s_barrier()
; #define PG8_SCHED __builtin_amdgcn_sched_barrier(0)
; template <class Epi>
; DI void gemm_phase(LAS unsigned char* lds, const Gemm g, const StaticOrder& S, const Epi& E) {
;     ...
;             PG8_STAGE(PG8_SB(0, 1), b2 + hstepB, voffB);
;             PG8_WAIT_V(6); PG8_BAR; PG8_MMA(1, 1, At, B1); PG8_BAR;
;             PG8_LDB(B0, 1, 0); PG8_SCHED; PG8_LDA(At, 1, 0); PG8_STAGE(PG8_SA(0, 1), a2 + hstepA, voffA);
;             PG8_WAIT_L(8); PG8_BAR; PG8_WAIT_L(0); PG8_MMA(0, 0, At, B0); PG8_BAR; PG8_SCHED;
;             PG8_LDB(B1, 1, 1); PG8_STAGE(PG8_SB(1, 0), b3, voffB);
;             PG8_BAR; PG8_WAIT_L(0); PG8_MMA(0, 1, At, B1); PG8_BAR;
;             PG8_LDA(At, 1, 1); PG8_STAGE(PG8_SA(1, 0), a3, voffA);
;             PG8_BAR; PG8_WAIT_L(0); PG8_MMA(1, 0, At, B0); PG8_BAR; PG8_SCHED;
	s_add_u32 s0, s38, 0x100000
	s_addc_u32 s1, s39, 0
	s_add_i32 s63, s57, s33
	v_lshl_add_u64 v[2:3], s[0:1], 0, v[190:191]
	s_mov_b32 m0, s63
	s_nop 0
	global_load_lds_dwordx4 v[2:3], off
	v_lshl_add_u64 v[2:3], s[0:1], 0, v[194:195]
	s_add_i32 m0, s63, 0x2000
	s_nop 0
	global_load_lds_dwordx4 v[2:3], off
	s_waitcnt vmcnt(6)
	s_barrier
	s_setprio 1
	v_mfma_f32_16x16x32_bf16 v[56:59], v[180:183], v[148:151], v[56:59]
	v_mfma_f32_16x16x32_bf16 v[52:55], v[210:213], v[148:151], v[52:55]
	v_mfma_f32_16x16x32_bf16 v[40:43], v[180:183], v[156:159], v[40:43]
	v_mfma_f32_16x16x32_bf16 v[36:39], v[210:213], v[156:159], v[36:39]
	v_mfma_f32_16x16x32_bf16 v[24:27], v[180:183], v[164:167], v[24:27]
	v_mfma_f32_16x16x32_bf16 v[20:23], v[210:213], v[164:167], v[20:23]
	v_mfma_f32_16x16x32_bf16 v[8:11], v[180:183], v[172:175], v[8:11]
	v_mfma_f32_16x16x32_bf16 v[2:5], v[210:213], v[172:175], v[4:7]
	v_mfma_f32_16x16x32_bf16 v[56:59], v[184:187], v[152:155], v[56:59]
	v_mfma_f32_16x16x32_bf16 v[52:55], v[224:227], v[152:155], v[52:55]
	v_mfma_f32_16x16x32_bf16 v[40:43], v[184:187], v[160:163], v[40:43]
	v_mfma_f32_16x16x32_bf16 v[36:39], v[224:227], v[160:163], v[36:39]
	v_mfma_f32_16x16x32_bf16 v[24:27], v[184:187], v[168:171], v[24:27]
	v_mfma_f32_16x16x32_bf16 v[20:23], v[224:227], v[168:171], v[20:23]
	v_mfma_f32_16x16x32_bf16 v[8:11], v[184:187], v[176:179], v[8:11]
	v_mfma_f32_16x16x32_bf16 v[2:5], v[224:227], v[176:179], v[2:5]
	s_setprio 0
	s_add_i32 s63, 0, 0x18000
	v_add_u32_e32 v1, s63, v219
	s_barrier
	ds_read_b128 v[132:135], v1
	ds_read_b128 v[136:139], v1 offset:1024
	ds_read_b128 v[140:143], v1 offset:2048
	ds_read_b128 v[144:147], v1 offset:3072
	s_add_u32 s0, s40, 0x100000
	s_addc_u32 s1, s41, 0
	s_mov_b32 m0, s46
	v_lshl_add_u64 v[6:7], s[0:1], 0, v[188:189]
	ds_read_b128 v[148:151], v222 offset:32768
	ds_read_b128 v[152:155], v222 offset:33792
	ds_read_b128 v[156:159], v222 offset:34816
	ds_read_b128 v[160:163], v222 offset:35840
	ds_read_b128 v[164:167], v222 offset:36864
	ds_read_b128 v[168:171], v222 offset:37888
	ds_read_b128 v[172:175], v222 offset:38912
	ds_read_b128 v[176:179], v222 offset:39936
	global_load_lds_dwordx4 v[6:7], off
	v_lshl_add_u64 v[6:7], s[0:1], 0, v[192:193]
	s_mov_b32 m0, s47
	s_nop 0
	global_load_lds_dwordx4 v[6:7], off
	s_waitcnt lgkmcnt(8)
	s_barrier
	s_waitcnt lgkmcnt(0)
	s_setprio 1
	s_waitcnt lgkmcnt(0)
	v_mfma_f32_16x16x32_bf16 v[128:131], v[132:135], v[148:151], v[128:131]
	v_mfma_f32_16x16x32_bf16 v[124:127], v[140:143], v[148:151], v[124:127]
	v_mfma_f32_16x16x32_bf16 v[112:115], v[132:135], v[156:159], v[112:115]
	v_mfma_f32_16x16x32_bf16 v[108:111], v[140:143], v[156:159], v[108:111]
	v_mfma_f32_16x16x32_bf16 v[96:99], v[132:135], v[164:167], v[96:99]
	v_mfma_f32_16x16x32_bf16 v[92:95], v[140:143], v[164:167], v[92:95]
	v_mfma_f32_16x16x32_bf16 v[80:83], v[132:135], v[172:175], v[80:83]
	v_mfma_f32_16x16x32_bf16 v[76:79], v[140:143], v[172:175], v[76:79]
	v_mfma_f32_16x16x32_bf16 v[128:131], v[136:139], v[152:155], v[128:131]
	v_mfma_f32_16x16x32_bf16 v[124:127], v[144:147], v[152:155], v[124:127]
	v_mfma_f32_16x16x32_bf16 v[112:115], v[136:139], v[160:163], v[112:115]
	v_mfma_f32_16x16x32_bf16 v[108:111], v[144:147], v[160:163], v[108:111]
	v_mfma_f32_16x16x32_bf16 v[96:99], v[136:139], v[168:171], v[96:99]
	v_mfma_f32_16x16x32_bf16 v[92:95], v[144:147], v[168:171], v[92:95]
	v_mfma_f32_16x16x32_bf16 v[80:83], v[136:139], v[176:179], v[80:83]
	v_mfma_f32_16x16x32_bf16 v[76:79], v[144:147], v[176:179], v[76:79]
	s_setprio 0
	s_barrier
	s_add_i32 s40, 0, 0x1c000
	s_add_i32 s0, s63, s33
	v_add_u32_e32 v1, s40, v219
	v_lshl_add_u64 v[6:7], v[228:229], 0, s[16:17]
	s_mov_b32 m0, s0
	ds_read_b128 v[180:183], v1
	ds_read_b128 v[184:187], v1 offset:1024
	ds_read_b128 v[210:213], v1 offset:2048
	ds_read_b128 v[224:227], v1 offset:3072
	global_load_lds_dwordx4 v[6:7], off
	v_lshl_add_u64 v[6:7], v[230:231], 0, s[16:17]
	s_add_i32 m0, s0, 0x2000
	s_nop 0
	global_load_lds_dwordx4 v[6:7], off
	s_barrier
; #define PG8_STAGE(bufoff, gbase, voff) do { _Pragma("unroll") for (int _i = 0; _i < 2; ++_i) \
;         __builtin_amdgcn_global_load_lds((const unsigned*)((const char*)(gbase) + (voff)[_i]), (LAS unsigned*)(lds + (bufoff) + ldsw + _i * 8192), 16, 0, 0); } while (0)
; #define PG8_LDA(dst, b, h) do { _Pragma("unroll") for (int m = 0; m < 4; ++m) _Pragma("unroll") for (int k = 0; k < 2; ++k) dst[m][k] = *(const LAS bf16x8*)(lds + PG8_SA(b, h) + aoff + m * 2048 + k * 1024); } while (0)
; #define PG8_LDB(dst, b, h) do { _Pragma("unroll") for (int n = 0; n < 2; ++n) _Pragma("unroll") for (int k = 0; k < 2; ++k) dst[n][k] = *(const LAS bf16x8*)(lds + PG8_SB(b, h) + boff + n * 2048 + k * 1024); } while (0)
; #define PG8_MMA(ai, bj, At, Bt) do { __builtin_amdgcn_s_setprio(1); _Pragma("unroll") for (int m = 0; m < 4; ++m) _Pragma("unroll") for (int n = 0; n < 2; ++n) _Pragma("unroll") for (int k = 0; k < 2; ++k) \
;         acc[ai][bj][m][n] = __builtin_amdgcn_mfma_f32_16x16x32_bf16(Bt[n][k], At[m][k], acc[ai][bj][m][n], 0, 0, 0); __builtin_amdgcn_s_setprio(0); } while (0)
; #define PG8_WAIT_V(n) asm volatile("s_waitcnt vmcnt(" #n ")" ::: "memory")
; #define PG8_WAIT_L(n) asm volatile("s_waitcnt lgkmcnt(" #n ")" ::: "memory")
; #define PG8_BAR __builtin_amdgcn_s_barrier()
; #define PG8_SCHED __builtin_amdgcn_sched_barrier(0)
; template <class Epi>
; DI void gemm_phase(LAS unsigned char* lds, const Gemm g, const StaticOrder& S, const Epi& E) {
;     ...
;             PG8_LDB(B1, 1, 1); PG8_STAGE(PG8_SB(1, 0), b3, voffB);
;             PG8_BAR; PG8_WAIT_L(0); PG8_MMA(0, 1, At, B1); PG8_BAR;
;             PG8_LDA(At, 1, 1); PG8_STAGE(PG8_SA(1, 0), a3, voffA);
;             PG8_BAR; PG8_WAIT_L(0); PG8_MMA(1, 0, At, B0); PG8_BAR; PG8_SCHED;
;             PG8_STAGE(PG8_SB(1, 1), b3 + hstepB, voffB);
;             PG8_WAIT_V(6); PG8_BAR; PG8_MMA(1, 1, At, B1); PG8_BAR;
	s_waitcnt lgkmcnt(0)
	s_setprio 1
	s_waitcnt lgkmcnt(0)
	v_mfma_f32_16x16x32_bf16 v[120:123], v[180:183], v[148:151], v[120:123]
	v_mfma_f32_16x16x32_bf16 v[116:119], v[210:213], v[148:151], v[116:119]
	v_mfma_f32_16x16x32_bf16 v[104:107], v[180:183], v[156:159], v[104:107]
	v_mfma_f32_16x16x32_bf16 v[100:103], v[210:213], v[156:159], v[100:103]
	v_mfma_f32_16x16x32_bf16 v[88:91], v[180:183], v[164:167], v[88:91]
	v_mfma_f32_16x16x32_bf16 v[84:87], v[210:213], v[164:167], v[84:87]
	v_mfma_f32_16x16x32_bf16 v[72:75], v[180:183], v[172:175], v[72:75]
	v_mfma_f32_16x16x32_bf16 v[68:71], v[210:213], v[172:175], v[68:71]
	v_mfma_f32_16x16x32_bf16 v[120:123], v[184:187], v[152:155], v[120:123]
	v_mfma_f32_16x16x32_bf16 v[116:119], v[224:227], v[152:155], v[116:119]
	v_mfma_f32_16x16x32_bf16 v[104:107], v[184:187], v[160:163], v[104:107]
	v_mfma_f32_16x16x32_bf16 v[100:103], v[224:227], v[160:163], v[100:103]
	v_mfma_f32_16x16x32_bf16 v[88:91], v[184:187], v[168:171], v[88:91]
	v_mfma_f32_16x16x32_bf16 v[84:87], v[224:227], v[168:171], v[84:87]
	v_mfma_f32_16x16x32_bf16 v[72:75], v[184:187], v[176:179], v[72:75]
	v_mfma_f32_16x16x32_bf16 v[68:71], v[224:227], v[176:179], v[68:71]
	s_setprio 0
	s_mov_b32 m0, s50
	v_lshl_add_u64 v[6:7], v[232:233], 0, s[16:17]
	s_barrier
	ds_read_b128 v[148:151], v222 offset:49152
	ds_read_b128 v[152:155], v222 offset:50176
	ds_read_b128 v[156:159], v222 offset:51200
	ds_read_b128 v[160:163], v222 offset:52224
	ds_read_b128 v[164:167], v222 offset:53248
	ds_read_b128 v[168:171], v222 offset:54272
	ds_read_b128 v[172:175], v222 offset:55296
	ds_read_b128 v[176:179], v222 offset:56320
	global_load_lds_dwordx4 v[6:7], off
	v_lshl_add_u64 v[6:7], v[234:235], 0, s[16:17]
	s_mov_b32 m0, s51
	s_nop 0
	global_load_lds_dwordx4 v[6:7], off
	s_barrier
	s_waitcnt lgkmcnt(0)
	s_setprio 1
	s_waitcnt lgkmcnt(0)
	v_mfma_f32_16x16x32_bf16 v[64:67], v[132:135], v[148:151], v[64:67]
	v_mfma_f32_16x16x32_bf16 v[60:63], v[140:143], v[148:151], v[60:63]
	v_mfma_f32_16x16x32_bf16 v[48:51], v[132:135], v[156:159], v[48:51]
	v_mfma_f32_16x16x32_bf16 v[44:47], v[140:143], v[156:159], v[44:47]
	v_mfma_f32_16x16x32_bf16 v[32:35], v[132:135], v[164:167], v[32:35]
	v_mfma_f32_16x16x32_bf16 v[28:31], v[140:143], v[164:167], v[28:31]
	v_mfma_f32_16x16x32_bf16 v[16:19], v[132:135], v[172:175], v[16:19]
	v_mfma_f32_16x16x32_bf16 v[12:15], v[140:143], v[172:175], v[12:15]
	v_mfma_f32_16x16x32_bf16 v[64:67], v[136:139], v[152:155], v[64:67]
	v_mfma_f32_16x16x32_bf16 v[60:63], v[144:147], v[152:155], v[60:63]
	v_mfma_f32_16x16x32_bf16 v[48:51], v[136:139], v[160:163], v[48:51]
	v_mfma_f32_16x16x32_bf16 v[44:47], v[144:147], v[160:163], v[44:47]
	v_mfma_f32_16x16x32_bf16 v[32:35], v[136:139], v[168:171], v[32:35]
	v_mfma_f32_16x16x32_bf16 v[28:31], v[144:147], v[168:171], v[28:31]
	v_mfma_f32_16x16x32_bf16 v[16:19], v[136:139], v[176:179], v[16:19]
	v_mfma_f32_16x16x32_bf16 v[12:15], v[144:147], v[176:179], v[12:15]
	s_setprio 0
	s_barrier
	s_add_u32 s0, s38, 0x100080
	s_addc_u32 s1, s39, 0
	s_add_i32 s38, s40, s33
	v_lshl_add_u64 v[6:7], s[0:1], 0, v[190:191]
	s_mov_b32 m0, s38
	s_nop 0
	global_load_lds_dwordx4 v[6:7], off
	v_lshl_add_u64 v[6:7], s[0:1], 0, v[194:195]
	s_add_i32 m0, s38, 0x2000
	s_nop 0
	global_load_lds_dwordx4 v[6:7], off
	s_waitcnt vmcnt(6)
	s_barrier
	s_setprio 1
	v_mfma_f32_16x16x32_bf16 v[56:59], v[180:183], v[148:151], v[56:59]
	v_mfma_f32_16x16x32_bf16 v[52:55], v[210:213], v[148:151], v[52:55]
	v_mfma_f32_16x16x32_bf16 v[40:43], v[180:183], v[156:159], v[40:43]
	v_mfma_f32_16x16x32_bf16 v[36:39], v[210:213], v[156:159], v[36:39]
	v_mfma_f32_16x16x32_bf16 v[24:27], v[180:183], v[164:167], v[24:27]
	v_mfma_f32_16x16x32_bf16 v[20:23], v[210:213], v[164:167], v[20:23]
	v_mfma_f32_16x16x32_bf16 v[6:9], v[180:183], v[172:175], v[8:11]
	v_mfma_f32_16x16x32_bf16 v[2:5], v[210:213], v[172:175], v[2:5]
	v_mfma_f32_16x16x32_bf16 v[56:59], v[184:187], v[152:155], v[56:59]
	v_mfma_f32_16x16x32_bf16 v[52:55], v[224:227], v[152:155], v[52:55]
	v_mfma_f32_16x16x32_bf16 v[40:43], v[184:187], v[160:163], v[40:43]
	v_mfma_f32_16x16x32_bf16 v[36:39], v[224:227], v[160:163], v[36:39]
	v_mfma_f32_16x16x32_bf16 v[24:27], v[184:187], v[168:171], v[24:27]
	v_mfma_f32_16x16x32_bf16 v[20:23], v[224:227], v[168:171], v[20:23]
	v_mfma_f32_16x16x32_bf16 v[8:11], v[184:187], v[176:179], v[6:9]
	v_mfma_f32_16x16x32_bf16 v[4:7], v[224:227], v[176:179], v[2:5]
	s_setprio 0
	s_add_i32 s62, s62, 2
	s_add_u32 s36, s36, 0x100
	s_addc_u32 s37, s37, 0
	s_cmp_gt_u32 s62, 61
	s_barrier
	s_cbranch_scc1 .LBB0_622
